# w_in and q epilogues: ssq panel staged in LDS like the swiglu epilogue (no vmcnt(0) on the next unit's tile prefetch)
# baseline (speedup 1.0000x reference)
.Lpeel_523:
	s_add_i32 s56, s42, 2
	s_add_u32 s29, s16, 0xfffc0080
	s_addc_u32 s37, s17, -1
	s_add_i32 s57, 0, 0x10000
	s_cmp_eq_u32 s84, s42
	s_cselect_b32 s45, s13, s37
	s_cselect_b32 s44, s15, s29
	v_add_u32_e32 v0, s57, v195
	s_cselect_b32 s43, s38, s49
	s_cselect_b32 s42, s39, s48
	s_add_i32 s29, 0, 0x14000
	ds_read_b128 v[130:133], v0
	ds_read_b128 v[150:153], v0 offset:1024
	ds_read_b128 v[154:157], v0 offset:2048
	ds_read_b128 v[158:161], v0 offset:3072
	v_add_u32_e32 v0, s29, v195
	ds_read_b128 v[174:177], v0
	ds_read_b128 v[178:181], v0 offset:1024
	ds_read_b128 v[182:185], v0 offset:2048
	ds_read_b128 v[186:189], v0 offset:3072
	s_add_i32 m0, s5, 0xc000
	ds_read_b128 v[190:193], v196
	ds_read_b128 v[204:207], v196 offset:1024
	ds_read_b128 v[208:211], v196 offset:2048
	ds_read_b128 v[212:215], v196 offset:3072
	ds_read_b128 v[216:219], v196 offset:4096
	ds_read_b128 v[220:223], v196 offset:5120
	ds_read_b128 v[224:227], v196 offset:6144
	ds_read_b128 v[228:231], v196 offset:7168
	global_load_lds_dwordx4 v146, s[16:17]
	s_add_i32 m0, s5, 0xe000
	s_nop 0
	global_load_lds_dwordx4 v148, s[16:17]
	s_waitcnt vmcnt(8)
	s_waitcnt lgkmcnt(0)
	s_setprio 1
	s_barrier
	v_mfma_f32_16x16x32_bf16 v[126:129], v[130:133], v[190:193], 0
	v_mfma_f32_16x16x32_bf16 v[122:125], v[154:157], v[190:193], 0
	v_mfma_f32_16x16x32_bf16 v[110:113], v[130:133], v[208:211], 0
	v_mfma_f32_16x16x32_bf16 v[106:109], v[154:157], v[208:211], 0
	v_mfma_f32_16x16x32_bf16 v[94:97], v[130:133], v[216:219], 0
	v_mfma_f32_16x16x32_bf16 v[90:93], v[154:157], v[216:219], 0
	v_mfma_f32_16x16x32_bf16 v[78:81], v[130:133], v[224:227], 0
	v_mfma_f32_16x16x32_bf16 v[74:77], v[154:157], v[224:227], 0
	v_mfma_f32_16x16x32_bf16 v[126:129], v[150:153], v[204:207], v[126:129]
	v_mfma_f32_16x16x32_bf16 v[122:125], v[158:161], v[204:207], v[122:125]
	v_mfma_f32_16x16x32_bf16 v[110:113], v[150:153], v[212:215], v[110:113]
	v_mfma_f32_16x16x32_bf16 v[106:109], v[158:161], v[212:215], v[106:109]
	v_mfma_f32_16x16x32_bf16 v[94:97], v[150:153], v[220:223], v[94:97]
	v_mfma_f32_16x16x32_bf16 v[90:93], v[158:161], v[220:223], v[90:93]
	v_mfma_f32_16x16x32_bf16 v[78:81], v[150:153], v[228:231], v[78:81]
	v_mfma_f32_16x16x32_bf16 v[74:77], v[158:161], v[228:231], v[74:77]
	v_mfma_f32_16x16x32_bf16 v[118:121], v[174:177], v[190:193], 0
	v_mfma_f32_16x16x32_bf16 v[114:117], v[182:185], v[190:193], 0
	v_mfma_f32_16x16x32_bf16 v[102:105], v[174:177], v[208:211], 0
	v_mfma_f32_16x16x32_bf16 v[98:101], v[182:185], v[208:211], 0
	v_mfma_f32_16x16x32_bf16 v[86:89], v[174:177], v[216:219], 0
	v_mfma_f32_16x16x32_bf16 v[82:85], v[182:185], v[216:219], 0
	v_mfma_f32_16x16x32_bf16 v[70:73], v[174:177], v[224:227], 0
	v_mfma_f32_16x16x32_bf16 v[66:69], v[182:185], v[224:227], 0
	v_mfma_f32_16x16x32_bf16 v[118:121], v[178:181], v[204:207], v[118:121]
	v_mfma_f32_16x16x32_bf16 v[114:117], v[186:189], v[204:207], v[114:117]
	v_mfma_f32_16x16x32_bf16 v[102:105], v[178:181], v[212:215], v[102:105]
	v_mfma_f32_16x16x32_bf16 v[98:101], v[186:189], v[212:215], v[98:101]
	v_mfma_f32_16x16x32_bf16 v[86:89], v[178:181], v[220:223], v[86:89]
	v_mfma_f32_16x16x32_bf16 v[82:85], v[186:189], v[220:223], v[82:85]
	v_mfma_f32_16x16x32_bf16 v[70:73], v[178:181], v[228:231], v[70:73]
	v_mfma_f32_16x16x32_bf16 v[66:69], v[186:189], v[228:231], v[66:69]
	s_barrier
	s_setprio 0
	s_add_i32 s37, s57, s4
	v_lshl_add_u64 v[170:171], s[42:43], 0, v[138:139]
	s_mov_b32 m0, s37
	ds_read_b128 v[190:193], v196 offset:16384
	ds_read_b128 v[204:207], v196 offset:17408
	ds_read_b128 v[208:211], v196 offset:18432
	ds_read_b128 v[212:215], v196 offset:19456
	ds_read_b128 v[216:219], v196 offset:20480
	ds_read_b128 v[220:223], v196 offset:21504
	ds_read_b128 v[224:227], v196 offset:22528
	ds_read_b128 v[228:231], v196 offset:23552
	global_load_lds_dwordx4 v[170:171], off
	s_add_i32 m0, s37, 0x2000
	s_add_u32 s74, s42, 0x40000
	v_lshl_add_u64 v[172:173], s[42:43], 0, v[134:135]
	s_addc_u32 s75, s43, 0
	s_add_i32 s29, s29, s4
	global_load_lds_dwordx4 v[172:173], off
	s_mov_b32 m0, s29
	v_lshl_add_u64 v[232:233], s[44:45], 0, v[136:137]
	global_load_lds_dwordx4 v138, s[74:75]
	s_add_i32 m0, s29, 0x2000
	s_nop 0
	global_load_lds_dwordx4 v134, s[74:75]
	v_lshl_add_u64 v[198:199], s[44:45], 0, v[140:141]
	s_mov_b32 m0, s5
	s_nop 0
	global_load_lds_dwordx4 v[198:199], off
	s_mov_b32 m0, s20
	s_nop 0
	global_load_lds_dwordx4 v[232:233], off
	s_lshl_b32 s101, s28, 14
	s_add_i32 s101, s101, s5
	s_add_u32 s100, s66, s101
	s_addc_u32 s101, s67, 0
	v_lshlrev_b32_e32 v2, 4, v163
	v_add_u32_e32 v3, 0x2000, v2
	s_add_i32 m0, s5, 0x20000
	s_nop 0
	global_load_lds_dwordx4 v2, s[100:101]
	s_add_i32 m0, s5, 0x22000
	s_nop 0
	global_load_lds_dwordx4 v3, s[100:101]
	s_waitcnt vmcnt(8)
	s_waitcnt lgkmcnt(0)
	s_setprio 1
	s_barrier
	v_mfma_f32_16x16x32_bf16 v[62:65], v[130:133], v[190:193], 0
	v_mfma_f32_16x16x32_bf16 v[58:61], v[154:157], v[190:193], 0
	v_mfma_f32_16x16x32_bf16 v[46:49], v[130:133], v[208:211], 0
	v_mfma_f32_16x16x32_bf16 v[42:45], v[154:157], v[208:211], 0
	v_mfma_f32_16x16x32_bf16 v[30:33], v[130:133], v[216:219], 0
	v_mfma_f32_16x16x32_bf16 v[26:29], v[154:157], v[216:219], 0
	v_mfma_f32_16x16x32_bf16 v[14:17], v[130:133], v[224:227], 0
	v_mfma_f32_16x16x32_bf16 v[10:13], v[154:157], v[224:227], 0
	v_mfma_f32_16x16x32_bf16 v[62:65], v[150:153], v[204:207], v[62:65]
	v_mfma_f32_16x16x32_bf16 v[58:61], v[158:161], v[204:207], v[58:61]
	v_mfma_f32_16x16x32_bf16 v[46:49], v[150:153], v[212:215], v[46:49]
	v_mfma_f32_16x16x32_bf16 v[42:45], v[158:161], v[212:215], v[42:45]
	v_mfma_f32_16x16x32_bf16 v[30:33], v[150:153], v[220:223], v[30:33]
	v_mfma_f32_16x16x32_bf16 v[26:29], v[158:161], v[220:223], v[26:29]
	v_mfma_f32_16x16x32_bf16 v[14:17], v[150:153], v[228:231], v[14:17]
	v_mfma_f32_16x16x32_bf16 v[10:13], v[158:161], v[228:231], v[10:13]
	v_mfma_f32_16x16x32_bf16 v[54:57], v[174:177], v[190:193], 0
	v_mfma_f32_16x16x32_bf16 v[50:53], v[182:185], v[190:193], 0
	v_mfma_f32_16x16x32_bf16 v[38:41], v[174:177], v[208:211], 0
	v_mfma_f32_16x16x32_bf16 v[34:37], v[182:185], v[208:211], 0
	v_mfma_f32_16x16x32_bf16 v[22:25], v[174:177], v[216:219], 0
	v_mfma_f32_16x16x32_bf16 v[18:21], v[182:185], v[216:219], 0
	v_mfma_f32_16x16x32_bf16 v[6:9], v[174:177], v[224:227], 0
	v_mfma_f32_16x16x32_bf16 v[2:5], v[182:185], v[224:227], 0
	v_mfma_f32_16x16x32_bf16 v[54:57], v[178:181], v[204:207], v[54:57]
	v_mfma_f32_16x16x32_bf16 v[50:53], v[186:189], v[204:207], v[50:53]
	v_mfma_f32_16x16x32_bf16 v[38:41], v[178:181], v[212:215], v[38:41]
	v_mfma_f32_16x16x32_bf16 v[34:37], v[186:189], v[212:215], v[34:37]
	v_mfma_f32_16x16x32_bf16 v[22:25], v[178:181], v[220:223], v[22:25]
	v_mfma_f32_16x16x32_bf16 v[18:21], v[186:189], v[220:223], v[18:21]
	v_mfma_f32_16x16x32_bf16 v[6:9], v[178:181], v[228:231], v[6:9]
	v_mfma_f32_16x16x32_bf16 v[2:5], v[186:189], v[228:231], v[2:5]
	s_barrier
	s_setprio 0
	s_add_i32 s29, 0, 0x18000
	v_add_u32_e32 v0, s29, v195
	s_add_i32 s37, 0, 0x1c000
	ds_read_b128 v[130:133], v0
	ds_read_b128 v[150:153], v0 offset:1024
	ds_read_b128 v[154:157], v0 offset:2048
	ds_read_b128 v[158:161], v0 offset:3072
	v_add_u32_e32 v0, s37, v195
	ds_read_b128 v[174:177], v0
	ds_read_b128 v[178:181], v0 offset:1024
	ds_read_b128 v[182:185], v0 offset:2048
	ds_read_b128 v[186:189], v0 offset:3072
	s_add_u32 s44, s44, 0x40000
	s_addc_u32 s45, s45, 0
	s_mov_b32 m0, s22
	ds_read_b128 v[190:193], v196 offset:32768
	ds_read_b128 v[204:207], v196 offset:33792
	ds_read_b128 v[208:211], v196 offset:34816
	ds_read_b128 v[212:215], v196 offset:35840
	ds_read_b128 v[216:219], v196 offset:36864
	ds_read_b128 v[220:223], v196 offset:37888
	ds_read_b128 v[224:227], v196 offset:38912
	ds_read_b128 v[228:231], v196 offset:39936
	global_load_lds_dwordx4 v140, s[44:45]
	s_mov_b32 m0, s23
	s_nop 0
	global_load_lds_dwordx4 v136, s[44:45]
	s_waitcnt vmcnt(8)
	s_waitcnt lgkmcnt(0)
	s_setprio 1
	s_barrier
	v_mfma_f32_16x16x32_bf16 v[126:129], v[130:133], v[190:193], v[126:129]
	v_mfma_f32_16x16x32_bf16 v[122:125], v[154:157], v[190:193], v[122:125]
	v_mfma_f32_16x16x32_bf16 v[110:113], v[130:133], v[208:211], v[110:113]
	v_mfma_f32_16x16x32_bf16 v[106:109], v[154:157], v[208:211], v[106:109]
	v_mfma_f32_16x16x32_bf16 v[94:97], v[130:133], v[216:219], v[94:97]
	v_mfma_f32_16x16x32_bf16 v[90:93], v[154:157], v[216:219], v[90:93]
	v_mfma_f32_16x16x32_bf16 v[78:81], v[130:133], v[224:227], v[78:81]
	v_mfma_f32_16x16x32_bf16 v[74:77], v[154:157], v[224:227], v[74:77]
	v_mfma_f32_16x16x32_bf16 v[126:129], v[150:153], v[204:207], v[126:129]
	v_mfma_f32_16x16x32_bf16 v[122:125], v[158:161], v[204:207], v[122:125]
	v_mfma_f32_16x16x32_bf16 v[110:113], v[150:153], v[212:215], v[110:113]
	v_mfma_f32_16x16x32_bf16 v[106:109], v[158:161], v[212:215], v[106:109]
	v_mfma_f32_16x16x32_bf16 v[94:97], v[150:153], v[220:223], v[94:97]
	v_mfma_f32_16x16x32_bf16 v[90:93], v[158:161], v[220:223], v[90:93]
	v_mfma_f32_16x16x32_bf16 v[78:81], v[150:153], v[228:231], v[78:81]
	v_mfma_f32_16x16x32_bf16 v[74:77], v[158:161], v[228:231], v[74:77]
	v_mfma_f32_16x16x32_bf16 v[118:121], v[174:177], v[190:193], v[118:121]
	v_mfma_f32_16x16x32_bf16 v[114:117], v[182:185], v[190:193], v[114:117]
	v_mfma_f32_16x16x32_bf16 v[102:105], v[174:177], v[208:211], v[102:105]
	v_mfma_f32_16x16x32_bf16 v[98:101], v[182:185], v[208:211], v[98:101]
	v_mfma_f32_16x16x32_bf16 v[86:89], v[174:177], v[216:219], v[86:89]
	v_mfma_f32_16x16x32_bf16 v[82:85], v[182:185], v[216:219], v[82:85]
	v_mfma_f32_16x16x32_bf16 v[70:73], v[174:177], v[224:227], v[70:73]
	v_mfma_f32_16x16x32_bf16 v[66:69], v[182:185], v[224:227], v[66:69]
	v_mfma_f32_16x16x32_bf16 v[118:121], v[178:181], v[204:207], v[118:121]
	v_mfma_f32_16x16x32_bf16 v[114:117], v[186:189], v[204:207], v[114:117]
	v_mfma_f32_16x16x32_bf16 v[102:105], v[178:181], v[212:215], v[102:105]
	v_mfma_f32_16x16x32_bf16 v[98:101], v[186:189], v[212:215], v[98:101]
	v_mfma_f32_16x16x32_bf16 v[86:89], v[178:181], v[220:223], v[86:89]
	v_mfma_f32_16x16x32_bf16 v[82:85], v[186:189], v[220:223], v[82:85]
	v_mfma_f32_16x16x32_bf16 v[70:73], v[178:181], v[228:231], v[70:73]
	v_mfma_f32_16x16x32_bf16 v[66:69], v[186:189], v[228:231], v[66:69]
	s_barrier
	s_setprio 0
	s_add_i32 s29, s29, s4
	v_lshl_add_u64 v[170:171], v[170:171], 0, s[24:25]
	s_mov_b32 m0, s29
	ds_read_b128 v[190:193], v196 offset:49152
	ds_read_b128 v[204:207], v196 offset:50176
	ds_read_b128 v[208:211], v196 offset:51200
	ds_read_b128 v[212:215], v196 offset:52224
	ds_read_b128 v[216:219], v196 offset:53248
	ds_read_b128 v[220:223], v196 offset:54272
	ds_read_b128 v[224:227], v196 offset:55296
	ds_read_b128 v[228:231], v196 offset:56320
	global_load_lds_dwordx4 v[170:171], off
	s_add_i32 m0, s29, 0x2000
	s_add_u32 s42, s42, 0x40080
	v_lshl_add_u64 v[170:171], v[172:173], 0, s[24:25]
	s_addc_u32 s43, s43, 0
	s_add_i32 s29, s37, s4
	global_load_lds_dwordx4 v[170:171], off
	s_mov_b32 m0, s29
	s_nop 0
	global_load_lds_dwordx4 v138, s[42:43]
	s_add_i32 m0, s29, 0x2000
	s_nop 0
	global_load_lds_dwordx4 v134, s[42:43]
	v_lshl_add_u64 v[170:171], v[198:199], 0, s[24:25]
	s_mov_b32 m0, s33
	s_nop 0
	global_load_lds_dwordx4 v[170:171], off
	v_lshl_add_u64 v[170:171], v[232:233], 0, s[24:25]
	s_mov_b32 m0, s72
	s_nop 0
	global_load_lds_dwordx4 v[170:171], off
	s_waitcnt vmcnt(8)
	s_waitcnt lgkmcnt(0)
	s_setprio 1
	s_barrier
	v_mfma_f32_16x16x32_bf16 v[62:65], v[130:133], v[190:193], v[62:65]
	v_mfma_f32_16x16x32_bf16 v[58:61], v[154:157], v[190:193], v[58:61]
	v_mfma_f32_16x16x32_bf16 v[46:49], v[130:133], v[208:211], v[46:49]
	v_mfma_f32_16x16x32_bf16 v[42:45], v[154:157], v[208:211], v[42:45]
	v_mfma_f32_16x16x32_bf16 v[30:33], v[130:133], v[216:219], v[30:33]
	v_mfma_f32_16x16x32_bf16 v[26:29], v[154:157], v[216:219], v[26:29]
	v_mfma_f32_16x16x32_bf16 v[14:17], v[130:133], v[224:227], v[14:17]
	v_mfma_f32_16x16x32_bf16 v[10:13], v[154:157], v[224:227], v[10:13]
	v_mfma_f32_16x16x32_bf16 v[62:65], v[150:153], v[204:207], v[62:65]
	v_mfma_f32_16x16x32_bf16 v[58:61], v[158:161], v[204:207], v[58:61]
	v_mfma_f32_16x16x32_bf16 v[46:49], v[150:153], v[212:215], v[46:49]
	v_mfma_f32_16x16x32_bf16 v[42:45], v[158:161], v[212:215], v[42:45]
	v_mfma_f32_16x16x32_bf16 v[30:33], v[150:153], v[220:223], v[30:33]
	v_mfma_f32_16x16x32_bf16 v[26:29], v[158:161], v[220:223], v[26:29]
	v_mfma_f32_16x16x32_bf16 v[14:17], v[150:153], v[228:231], v[14:17]
	v_mfma_f32_16x16x32_bf16 v[10:13], v[158:161], v[228:231], v[10:13]
	v_mfma_f32_16x16x32_bf16 v[54:57], v[174:177], v[190:193], v[54:57]
	v_mfma_f32_16x16x32_bf16 v[50:53], v[182:185], v[190:193], v[50:53]
	v_mfma_f32_16x16x32_bf16 v[38:41], v[174:177], v[208:211], v[38:41]
	v_mfma_f32_16x16x32_bf16 v[34:37], v[182:185], v[208:211], v[34:37]
	v_mfma_f32_16x16x32_bf16 v[22:25], v[174:177], v[216:219], v[22:25]
	v_mfma_f32_16x16x32_bf16 v[18:21], v[182:185], v[216:219], v[18:21]
	v_mfma_f32_16x16x32_bf16 v[6:9], v[174:177], v[224:227], v[6:9]
	v_mfma_f32_16x16x32_bf16 v[2:5], v[182:185], v[224:227], v[2:5]
	v_mfma_f32_16x16x32_bf16 v[54:57], v[178:181], v[204:207], v[54:57]
	v_mfma_f32_16x16x32_bf16 v[50:53], v[186:189], v[204:207], v[50:53]
	v_mfma_f32_16x16x32_bf16 v[38:41], v[178:181], v[212:215], v[38:41]
	v_mfma_f32_16x16x32_bf16 v[34:37], v[186:189], v[212:215], v[34:37]
	v_mfma_f32_16x16x32_bf16 v[22:25], v[178:181], v[220:223], v[22:25]
	v_mfma_f32_16x16x32_bf16 v[18:21], v[186:189], v[220:223], v[18:21]
	v_mfma_f32_16x16x32_bf16 v[6:9], v[178:181], v[228:231], v[6:9]
	v_mfma_f32_16x16x32_bf16 v[2:5], v[186:189], v[228:231], v[2:5]
	s_barrier
	s_setprio 0
	s_add_u32 s16, s16, 0x100
	s_addc_u32 s17, s17, 0
	s_add_u32 s48, s48, 0x100
	s_addc_u32 s49, s49, 0
	s_cmp_ge_i32 s56, s3
	s_mov_b32 s42, s56
	s_cbranch_scc0 .LBB7_523
	s_branch .Lpeelx_523

.LBB7_526:
	v_and_b32_e32 v192, 0x30, v163
	v_lshl_add_u32 v192, v143, 6, v192
	v_add_u32_e32 v192, 0x20000, v192
	ds_read_b128 v[204:207], v192 offset:1024
	ds_read_b128 v[208:211], v192 offset:2048
	ds_read_b128 v[212:215], v192 offset:3072
	ds_read_b128 v[216:219], v192 offset:8192
	ds_read_b128 v[220:223], v192 offset:9216
	ds_read_b128 v[224:227], v192 offset:10240
	ds_read_b128 v[228:231], v192 offset:11264
	v_and_b32_e32 v130, 64, v163
	v_xor_b32_e32 v0, 16, v163
	v_add_u32_e32 v130, 64, v130
	v_cmp_lt_i32_e32 vcc, v0, v130
	v_lshl_add_u32 v184, s28, 8, v143
	v_ashrrev_i32_e32 v185, 31, v184
	v_cndmask_b32_e32 v0, v163, v0, vcc
	v_lshlrev_b32_e32 v191, 2, v0
	v_xor_b32_e32 v0, 32, v163
	v_cmp_lt_i32_e32 vcc, v0, v130
	v_lshlrev_b64 v[130:131], 6, v[184:185]
	v_lshl_add_u64 v[130:131], v[144:145], 0, v[130:131]
	ds_read_b128 v[130:133], v192
	v_or_b32_e32 v180, 16, v184
	v_ashrrev_i32_e32 v181, 31, v180
	v_cndmask_b32_e32 v0, v163, v0, vcc
	v_lshlrev_b32_e32 v0, 2, v0
	v_or_b32_e32 v178, 32, v184
	v_ashrrev_i32_e32 v179, 31, v178
	v_or_b32_e32 v158, 48, v184
	v_ashrrev_i32_e32 v159, 31, v158
	v_add_u32_e32 v156, 0x80, v184
	v_ashrrev_i32_e32 v157, 31, v156
	v_add_u32_e32 v154, 0x90, v184
	v_ashrrev_i32_e32 v155, 31, v154
	s_lshl_b32 s13, s10, 8
	s_or_b32 s10, s13, s31
	s_movk_i32 s15, 0x17f
	v_lshlrev_b64 v[192:193], 11, v[184:185]
	s_waitcnt lgkmcnt(0)
	v_mov_b32_e32 v150, v131
	v_mov_b32_e32 v151, v132
	v_mov_b32_e32 v131, v133
	v_pk_add_f32 v[150:151], v[150:151], v[130:131]
	v_lshlrev_b64 v[130:131], 6, v[180:181]
	v_lshl_add_u64 v[130:131], v[144:145], 0, v[130:131]
	v_mov_b64_e32 v[130:131], v[204:205]
	v_mov_b64_e32 v[132:133], v[206:207]
	v_mov_b32_e32 v152, v131
	v_mov_b32_e32 v153, v132
	v_mov_b32_e32 v131, v133
	v_pk_add_f32 v[130:131], v[152:153], v[130:131]
	v_mov_b32_e32 v133, v150
	v_mov_b32_e32 v132, v130
	v_mov_b32_e32 v150, v131
	v_pk_add_f32 v[130:131], v[132:133], v[150:151]
	v_mov_b32_e32 v133, v131
	s_nop 1
	v_permlane16_swap_b32_e32 v131, v133
	v_mov_b32_e32 v132, v130
	s_nop 1
	v_permlane16_swap_b32_e32 v130, v132
	s_waitcnt lgkmcnt(0)
	v_pk_add_f32 v[130:131], v[130:131], v[132:133]
	v_mov_b32_e32 v133, v131
	s_nop 1
	v_permlane32_swap_b32_e32 v131, v133
	v_mov_b32_e32 v132, v130
	s_nop 1
	v_permlane32_swap_b32_e32 v130, v132
	s_waitcnt lgkmcnt(0)
	v_pk_add_f32 v[130:131], v[130:131], v[132:133]
	s_nop 0
	v_pk_fma_f32 v[188:189], v[130:131], s[26:27], v[162:163] op_sel_hi:[1,0,0]
	s_nop 0
	v_mul_f32_e32 v130, 0x4b800000, v189
	v_cmp_gt_f32_e32 vcc, s11, v189
	v_cmp_gt_f32_e64 s[44:45], s11, v188
	s_nop 0
	v_cndmask_b32_e32 v130, v189, v130, vcc
	v_rsq_f32_e32 v130, v130
	s_nop 0
	v_mul_f32_e32 v131, 0x45800000, v130
	v_cndmask_b32_e32 v190, v130, v131, vcc
	v_lshlrev_b64 v[130:131], 6, v[178:179]
	v_lshl_add_u64 v[130:131], v[144:145], 0, v[130:131]
	v_pk_mul_f32 v[128:129], v[128:129], v[190:191] op_sel_hi:[1,0]
	v_pk_mul_f32 v[126:127], v[126:127], v[190:191] op_sel_hi:[1,0]
	v_mov_b64_e32 v[130:131], v[208:209]
	v_mov_b64_e32 v[132:133], v[210:211]
	v_mov_b32_e32 v150, v131
	v_mov_b32_e32 v151, v132
	v_mov_b32_e32 v131, v133
	v_pk_add_f32 v[150:151], v[150:151], v[130:131]
	v_lshlrev_b64 v[130:131], 6, v[158:159]
	v_lshl_add_u64 v[130:131], v[144:145], 0, v[130:131]
	v_mov_b64_e32 v[130:131], v[212:213]
	v_mov_b64_e32 v[132:133], v[214:215]
	v_mov_b32_e32 v152, v131
	v_mov_b32_e32 v153, v132
	v_mov_b32_e32 v131, v133
	v_pk_add_f32 v[130:131], v[152:153], v[130:131]
	v_mov_b32_e32 v133, v150
	v_mov_b32_e32 v132, v130
	v_mov_b32_e32 v150, v131
	v_pk_add_f32 v[130:131], v[132:133], v[150:151]
	v_mov_b32_e32 v133, v131
	s_nop 1
	v_permlane16_swap_b32_e32 v131, v133
	v_mov_b32_e32 v132, v130
	s_nop 1
	v_permlane16_swap_b32_e32 v130, v132
	s_waitcnt lgkmcnt(0)
	v_pk_add_f32 v[182:183], v[130:131], v[132:133]
	v_lshlrev_b64 v[130:131], 6, v[156:157]
	v_lshl_add_u64 v[130:131], v[144:145], 0, v[130:131]
	ds_bpermute_b32 v187, v0, v183
	ds_bpermute_b32 v186, v0, v182
	v_mov_b64_e32 v[130:131], v[216:217]
	v_mov_b64_e32 v[132:133], v[218:219]
	v_mov_b32_e32 v150, v131
	v_mov_b32_e32 v151, v132
	v_mov_b32_e32 v131, v133
	v_pk_add_f32 v[150:151], v[150:151], v[130:131]
	v_lshlrev_b64 v[130:131], 6, v[154:155]
	v_lshl_add_u64 v[130:131], v[144:145], 0, v[130:131]
	v_mov_b64_e32 v[130:131], v[220:221]
	v_mov_b64_e32 v[132:133], v[222:223]
	v_mov_b32_e32 v152, v131
	v_mov_b32_e32 v153, v132
	v_mov_b32_e32 v131, v133
	v_pk_add_f32 v[130:131], v[152:153], v[130:131]
	v_mov_b32_e32 v133, v150
	v_mov_b32_e32 v132, v130
	v_mov_b32_e32 v150, v131
	v_pk_add_f32 v[130:131], v[132:133], v[150:151]
	v_mov_b32_e32 v133, v131
	s_nop 1
	v_permlane16_swap_b32_e32 v131, v133
	v_mov_b32_e32 v132, v130
	s_nop 1
	v_permlane16_swap_b32_e32 v130, v132
	v_add_u32_e32 v152, 0xa0, v184
	v_ashrrev_i32_e32 v153, 31, v152
	s_waitcnt lgkmcnt(0)
	v_pk_add_f32 v[160:161], v[130:131], v[132:133]
	v_lshlrev_b64 v[130:131], 6, v[152:153]
	v_lshl_add_u64 v[130:131], v[144:145], 0, v[130:131]
	ds_bpermute_b32 v175, v0, v161
	ds_bpermute_b32 v174, v0, v160
	v_mov_b64_e32 v[130:131], v[224:225]
	v_mov_b64_e32 v[132:133], v[226:227]
	v_mov_b32_e32 v150, v131
	v_mov_b32_e32 v151, v132
	v_mov_b32_e32 v131, v133
	v_pk_add_f32 v[176:177], v[150:151], v[130:131]
	v_add_u32_e32 v150, 0xb0, v184
	v_ashrrev_i32_e32 v151, 31, v150
	v_lshlrev_b64 v[130:131], 6, v[150:151]
	v_lshl_add_u64 v[130:131], v[144:145], 0, v[130:131]
	v_mov_b64_e32 v[130:131], v[228:229]
	v_mov_b64_e32 v[132:133], v[230:231]
	v_mov_b32_e32 v170, v131
	v_mov_b32_e32 v171, v132
	v_mov_b32_e32 v131, v133
	v_pk_add_f32 v[130:131], v[170:171], v[130:131]
	v_mov_b32_e32 v133, v176
	v_mov_b32_e32 v132, v130
	v_mov_b32_e32 v176, v131
	v_pk_add_f32 v[130:131], v[132:133], v[176:177]
	v_mov_b32_e32 v133, v131
	s_nop 1
	v_permlane16_swap_b32_e32 v131, v133
	v_mov_b32_e32 v132, v130
	s_nop 1
	v_permlane16_swap_b32_e32 v130, v132
	v_pk_mul_f32 v[170:171], v[124:125], v[190:191] op_sel_hi:[1,0]
	v_pk_mul_f32 v[124:125], v[122:123], v[190:191] op_sel_hi:[1,0]
	v_cvt_pk_bf16_f32 v122, v126, v127
	v_cvt_pk_bf16_f32 v123, v128, v129
	s_waitcnt lgkmcnt(0)
	v_pk_add_f32 v[132:133], v[130:131], v[132:133]
	ds_bpermute_b32 v177, v0, v133
	ds_bpermute_b32 v176, v0, v132
	v_or_b32_e32 v130, s10, v194
	v_cmp_lt_i32_e64 s[42:43], s15, v130
	v_cvt_pk_bf16_f32 v124, v124, v125
	v_cvt_pk_bf16_f32 v125, v170, v171
	s_and_saveexec_b64 s[16:17], s[42:43]
	s_xor_b64 s[16:17], exec, s[16:17]
	s_cbranch_execz .LBB7_529
	s_cmpk_gt_u32 s13, 0x57f
	s_cbranch_scc1 .LBB7_529
	v_lshl_add_u64 v[126:127], s[94:95], 0, v[192:193]
	v_mov_b32_e32 v131, v1
	v_lshl_add_u64 v[126:127], v[130:131], 1, v[126:127]
	global_store_dwordx4 v[126:127], v[122:125], off offset:-768

.Lpeel_1196:
	s_add_i32 s72, s42, 2
	s_add_u32 s29, s16, 0xfffc0080
	s_addc_u32 s37, s17, -1
	s_add_i32 s73, 0, 0x10000
	s_cmp_eq_u32 s55, s42
	s_cselect_b32 s53, s13, s37
	s_cselect_b32 s52, s15, s29
	v_add_u32_e32 v146, s73, v153
	s_cselect_b32 s43, s28, s57
	s_cselect_b32 s42, s39, s56
	s_add_i32 s29, 0, 0x14000
	ds_read_b128 v[130:133], v146
	ds_read_b128 v[156:159], v146 offset:1024
	ds_read_b128 v[174:177], v146 offset:2048
	ds_read_b128 v[178:181], v146 offset:3072
	v_add_u32_e32 v146, s29, v153
	ds_read_b128 v[182:185], v146
	ds_read_b128 v[186:189], v146 offset:1024
	ds_read_b128 v[190:193], v146 offset:2048
	ds_read_b128 v[194:197], v146 offset:3072
	s_add_i32 m0, s5, 0xc000
	ds_read_b128 v[204:207], v161
	ds_read_b128 v[208:211], v161 offset:1024
	ds_read_b128 v[212:215], v161 offset:2048
	ds_read_b128 v[216:219], v161 offset:3072
	ds_read_b128 v[220:223], v161 offset:4096
	ds_read_b128 v[224:227], v161 offset:5120
	ds_read_b128 v[228:231], v161 offset:6144
	ds_read_b128 v[232:235], v161 offset:7168
	global_load_lds_dwordx4 v142, s[16:17]
	s_add_i32 m0, s5, 0xe000
	s_nop 0
	global_load_lds_dwordx4 v144, s[16:17]
	s_waitcnt vmcnt(8)
	s_waitcnt lgkmcnt(0)
	s_setprio 1
	s_barrier
	v_mfma_f32_16x16x32_bf16 v[126:129], v[130:133], v[204:207], 0
	v_mfma_f32_16x16x32_bf16 v[122:125], v[174:177], v[204:207], 0
	v_mfma_f32_16x16x32_bf16 v[110:113], v[130:133], v[212:215], 0
	v_mfma_f32_16x16x32_bf16 v[106:109], v[174:177], v[212:215], 0
	v_mfma_f32_16x16x32_bf16 v[94:97], v[130:133], v[220:223], 0
	v_mfma_f32_16x16x32_bf16 v[90:93], v[174:177], v[220:223], 0
	v_mfma_f32_16x16x32_bf16 v[78:81], v[130:133], v[228:231], 0
	v_mfma_f32_16x16x32_bf16 v[74:77], v[174:177], v[228:231], 0
	v_mfma_f32_16x16x32_bf16 v[126:129], v[156:159], v[208:211], v[126:129]
	v_mfma_f32_16x16x32_bf16 v[122:125], v[178:181], v[208:211], v[122:125]
	v_mfma_f32_16x16x32_bf16 v[110:113], v[156:159], v[216:219], v[110:113]
	v_mfma_f32_16x16x32_bf16 v[106:109], v[178:181], v[216:219], v[106:109]
	v_mfma_f32_16x16x32_bf16 v[94:97], v[156:159], v[224:227], v[94:97]
	v_mfma_f32_16x16x32_bf16 v[90:93], v[178:181], v[224:227], v[90:93]
	v_mfma_f32_16x16x32_bf16 v[78:81], v[156:159], v[232:235], v[78:81]
	v_mfma_f32_16x16x32_bf16 v[74:77], v[178:181], v[232:235], v[74:77]
	v_mfma_f32_16x16x32_bf16 v[118:121], v[182:185], v[204:207], 0
	v_mfma_f32_16x16x32_bf16 v[114:117], v[190:193], v[204:207], 0
	v_mfma_f32_16x16x32_bf16 v[102:105], v[182:185], v[212:215], 0
	v_mfma_f32_16x16x32_bf16 v[98:101], v[190:193], v[212:215], 0
	v_mfma_f32_16x16x32_bf16 v[86:89], v[182:185], v[220:223], 0
	v_mfma_f32_16x16x32_bf16 v[82:85], v[190:193], v[220:223], 0
	v_mfma_f32_16x16x32_bf16 v[70:73], v[182:185], v[228:231], 0
	v_mfma_f32_16x16x32_bf16 v[66:69], v[190:193], v[228:231], 0
	v_mfma_f32_16x16x32_bf16 v[118:121], v[186:189], v[208:211], v[118:121]
	v_mfma_f32_16x16x32_bf16 v[114:117], v[194:197], v[208:211], v[114:117]
	v_mfma_f32_16x16x32_bf16 v[102:105], v[186:189], v[216:219], v[102:105]
	v_mfma_f32_16x16x32_bf16 v[98:101], v[194:197], v[216:219], v[98:101]
	v_mfma_f32_16x16x32_bf16 v[86:89], v[186:189], v[224:227], v[86:89]
	v_mfma_f32_16x16x32_bf16 v[82:85], v[194:197], v[224:227], v[82:85]
	v_mfma_f32_16x16x32_bf16 v[70:73], v[186:189], v[232:235], v[70:73]
	v_mfma_f32_16x16x32_bf16 v[66:69], v[194:197], v[232:235], v[66:69]
	s_barrier
	s_setprio 0
	s_add_i32 s37, s73, s4
	v_lshl_add_u64 v[146:147], s[42:43], 0, v[0:1]
	s_mov_b32 m0, s37
	ds_read_b128 v[204:207], v161 offset:16384
	ds_read_b128 v[208:211], v161 offset:17408
	ds_read_b128 v[212:215], v161 offset:18432
	ds_read_b128 v[216:219], v161 offset:19456
	ds_read_b128 v[220:223], v161 offset:20480
	ds_read_b128 v[224:227], v161 offset:21504
	ds_read_b128 v[228:231], v161 offset:22528
	ds_read_b128 v[232:235], v161 offset:23552
	global_load_lds_dwordx4 v[146:147], off
	s_add_i32 m0, s37, 0x2000
	s_add_u32 s74, s42, 0x40000
	v_lshl_add_u64 v[150:151], s[42:43], 0, v[134:135]
	s_addc_u32 s75, s43, 0
	s_add_i32 s29, s29, s4
	global_load_lds_dwordx4 v[150:151], off
	s_mov_b32 m0, s29
	v_lshl_add_u64 v[172:173], s[52:53], 0, v[136:137]
	global_load_lds_dwordx4 v0, s[74:75]
	s_add_i32 m0, s29, 0x2000
	s_nop 0
	global_load_lds_dwordx4 v134, s[74:75]
	v_lshl_add_u64 v[170:171], s[52:53], 0, v[138:139]
	s_mov_b32 m0, s5
	s_nop 0
	global_load_lds_dwordx4 v[170:171], off
	s_mov_b32 m0, s20
	s_nop 0
	global_load_lds_dwordx4 v[172:173], off
	s_lshl_b32 s101, s10, 14
	s_add_i32 s101, s101, s5
	s_add_u32 s100, s66, s101
	s_addc_u32 s101, s67, 0
	v_lshlrev_b32_e32 v2, 4, v163
	v_add_u32_e32 v3, 0x2000, v2
	s_add_i32 m0, s5, 0x20000
	s_nop 0
	global_load_lds_dwordx4 v2, s[100:101]
	s_add_i32 m0, s5, 0x22000
	s_nop 0
	global_load_lds_dwordx4 v3, s[100:101]
	s_waitcnt vmcnt(8)
	s_waitcnt lgkmcnt(0)
	s_setprio 1
	s_barrier
	v_mfma_f32_16x16x32_bf16 v[62:65], v[130:133], v[204:207], 0
	v_mfma_f32_16x16x32_bf16 v[58:61], v[174:177], v[204:207], 0
	v_mfma_f32_16x16x32_bf16 v[46:49], v[130:133], v[212:215], 0
	v_mfma_f32_16x16x32_bf16 v[42:45], v[174:177], v[212:215], 0
	v_mfma_f32_16x16x32_bf16 v[30:33], v[130:133], v[220:223], 0
	v_mfma_f32_16x16x32_bf16 v[26:29], v[174:177], v[220:223], 0
	v_mfma_f32_16x16x32_bf16 v[14:17], v[130:133], v[228:231], 0
	v_mfma_f32_16x16x32_bf16 v[10:13], v[174:177], v[228:231], 0
	v_mfma_f32_16x16x32_bf16 v[62:65], v[156:159], v[208:211], v[62:65]
	v_mfma_f32_16x16x32_bf16 v[58:61], v[178:181], v[208:211], v[58:61]
	v_mfma_f32_16x16x32_bf16 v[46:49], v[156:159], v[216:219], v[46:49]
	v_mfma_f32_16x16x32_bf16 v[42:45], v[178:181], v[216:219], v[42:45]
	v_mfma_f32_16x16x32_bf16 v[30:33], v[156:159], v[224:227], v[30:33]
	v_mfma_f32_16x16x32_bf16 v[26:29], v[178:181], v[224:227], v[26:29]
	v_mfma_f32_16x16x32_bf16 v[14:17], v[156:159], v[232:235], v[14:17]
	v_mfma_f32_16x16x32_bf16 v[10:13], v[178:181], v[232:235], v[10:13]
	v_mfma_f32_16x16x32_bf16 v[54:57], v[182:185], v[204:207], 0
	v_mfma_f32_16x16x32_bf16 v[50:53], v[190:193], v[204:207], 0
	v_mfma_f32_16x16x32_bf16 v[38:41], v[182:185], v[212:215], 0
	v_mfma_f32_16x16x32_bf16 v[34:37], v[190:193], v[212:215], 0
	v_mfma_f32_16x16x32_bf16 v[22:25], v[182:185], v[220:223], 0
	v_mfma_f32_16x16x32_bf16 v[18:21], v[190:193], v[220:223], 0
	v_mfma_f32_16x16x32_bf16 v[6:9], v[182:185], v[228:231], 0
	v_mfma_f32_16x16x32_bf16 v[2:5], v[190:193], v[228:231], 0
	v_mfma_f32_16x16x32_bf16 v[54:57], v[186:189], v[208:211], v[54:57]
	v_mfma_f32_16x16x32_bf16 v[50:53], v[194:197], v[208:211], v[50:53]
	v_mfma_f32_16x16x32_bf16 v[38:41], v[186:189], v[216:219], v[38:41]
	v_mfma_f32_16x16x32_bf16 v[34:37], v[194:197], v[216:219], v[34:37]
	v_mfma_f32_16x16x32_bf16 v[22:25], v[186:189], v[224:227], v[22:25]
	v_mfma_f32_16x16x32_bf16 v[18:21], v[194:197], v[224:227], v[18:21]
	v_mfma_f32_16x16x32_bf16 v[6:9], v[186:189], v[232:235], v[6:9]
	v_mfma_f32_16x16x32_bf16 v[2:5], v[194:197], v[232:235], v[2:5]
	s_barrier
	s_setprio 0
	s_add_i32 s29, 0, 0x18000
	v_add_u32_e32 v148, s29, v153
	s_add_i32 s37, 0, 0x1c000
	ds_read_b128 v[130:133], v148
	ds_read_b128 v[156:159], v148 offset:1024
	ds_read_b128 v[174:177], v148 offset:2048
	ds_read_b128 v[178:181], v148 offset:3072
	v_add_u32_e32 v148, s37, v153
	ds_read_b128 v[182:185], v148
	ds_read_b128 v[186:189], v148 offset:1024
	ds_read_b128 v[190:193], v148 offset:2048
	ds_read_b128 v[194:197], v148 offset:3072
	s_add_u32 s52, s52, 0x40000
	s_addc_u32 s53, s53, 0
	s_mov_b32 m0, s22
	ds_read_b128 v[204:207], v161 offset:32768
	ds_read_b128 v[208:211], v161 offset:33792
	ds_read_b128 v[212:215], v161 offset:34816
	ds_read_b128 v[216:219], v161 offset:35840
	ds_read_b128 v[220:223], v161 offset:36864
	ds_read_b128 v[224:227], v161 offset:37888
	ds_read_b128 v[228:231], v161 offset:38912
	ds_read_b128 v[232:235], v161 offset:39936
	global_load_lds_dwordx4 v138, s[52:53]
	s_mov_b32 m0, s23
	s_nop 0
	global_load_lds_dwordx4 v136, s[52:53]
	s_waitcnt vmcnt(8)
	s_waitcnt lgkmcnt(0)
	s_setprio 1
	s_barrier
	v_mfma_f32_16x16x32_bf16 v[126:129], v[130:133], v[204:207], v[126:129]
	v_mfma_f32_16x16x32_bf16 v[122:125], v[174:177], v[204:207], v[122:125]
	v_mfma_f32_16x16x32_bf16 v[110:113], v[130:133], v[212:215], v[110:113]
	v_mfma_f32_16x16x32_bf16 v[106:109], v[174:177], v[212:215], v[106:109]
	v_mfma_f32_16x16x32_bf16 v[94:97], v[130:133], v[220:223], v[94:97]
	v_mfma_f32_16x16x32_bf16 v[90:93], v[174:177], v[220:223], v[90:93]
	v_mfma_f32_16x16x32_bf16 v[78:81], v[130:133], v[228:231], v[78:81]
	v_mfma_f32_16x16x32_bf16 v[74:77], v[174:177], v[228:231], v[74:77]
	v_mfma_f32_16x16x32_bf16 v[126:129], v[156:159], v[208:211], v[126:129]
	v_mfma_f32_16x16x32_bf16 v[122:125], v[178:181], v[208:211], v[122:125]
	v_mfma_f32_16x16x32_bf16 v[110:113], v[156:159], v[216:219], v[110:113]
	v_mfma_f32_16x16x32_bf16 v[106:109], v[178:181], v[216:219], v[106:109]
	v_mfma_f32_16x16x32_bf16 v[94:97], v[156:159], v[224:227], v[94:97]
	v_mfma_f32_16x16x32_bf16 v[90:93], v[178:181], v[224:227], v[90:93]
	v_mfma_f32_16x16x32_bf16 v[78:81], v[156:159], v[232:235], v[78:81]
	v_mfma_f32_16x16x32_bf16 v[74:77], v[178:181], v[232:235], v[74:77]
	v_mfma_f32_16x16x32_bf16 v[118:121], v[182:185], v[204:207], v[118:121]
	v_mfma_f32_16x16x32_bf16 v[114:117], v[190:193], v[204:207], v[114:117]
	v_mfma_f32_16x16x32_bf16 v[102:105], v[182:185], v[212:215], v[102:105]
	v_mfma_f32_16x16x32_bf16 v[98:101], v[190:193], v[212:215], v[98:101]
	v_mfma_f32_16x16x32_bf16 v[86:89], v[182:185], v[220:223], v[86:89]
	v_mfma_f32_16x16x32_bf16 v[82:85], v[190:193], v[220:223], v[82:85]
	v_mfma_f32_16x16x32_bf16 v[70:73], v[182:185], v[228:231], v[70:73]
	v_mfma_f32_16x16x32_bf16 v[66:69], v[190:193], v[228:231], v[66:69]
	v_mfma_f32_16x16x32_bf16 v[118:121], v[186:189], v[208:211], v[118:121]
	v_mfma_f32_16x16x32_bf16 v[114:117], v[194:197], v[208:211], v[114:117]
	v_mfma_f32_16x16x32_bf16 v[102:105], v[186:189], v[216:219], v[102:105]
	v_mfma_f32_16x16x32_bf16 v[98:101], v[194:197], v[216:219], v[98:101]
	v_mfma_f32_16x16x32_bf16 v[86:89], v[186:189], v[224:227], v[86:89]
	v_mfma_f32_16x16x32_bf16 v[82:85], v[194:197], v[224:227], v[82:85]
	v_mfma_f32_16x16x32_bf16 v[70:73], v[186:189], v[232:235], v[70:73]
	v_mfma_f32_16x16x32_bf16 v[66:69], v[194:197], v[232:235], v[66:69]
	s_barrier
	s_setprio 0
	s_add_i32 s29, s29, s4
	v_lshl_add_u64 v[146:147], v[146:147], 0, s[24:25]
	s_mov_b32 m0, s29
	ds_read_b128 v[204:207], v161 offset:49152
	ds_read_b128 v[208:211], v161 offset:50176
	ds_read_b128 v[212:215], v161 offset:51200
	ds_read_b128 v[216:219], v161 offset:52224
	ds_read_b128 v[220:223], v161 offset:53248
	ds_read_b128 v[224:227], v161 offset:54272
	ds_read_b128 v[228:231], v161 offset:55296
	ds_read_b128 v[232:235], v161 offset:56320
	global_load_lds_dwordx4 v[146:147], off
	s_add_i32 m0, s29, 0x2000
	s_add_u32 s42, s42, 0x40080
	v_lshl_add_u64 v[146:147], v[150:151], 0, s[24:25]
	s_addc_u32 s43, s43, 0
	s_add_i32 s29, s37, s4
	global_load_lds_dwordx4 v[146:147], off
	s_mov_b32 m0, s29
	s_nop 0
	global_load_lds_dwordx4 v0, s[42:43]
	s_add_i32 m0, s29, 0x2000
	s_nop 0
	global_load_lds_dwordx4 v134, s[42:43]
	v_lshl_add_u64 v[146:147], v[170:171], 0, s[24:25]
	s_mov_b32 m0, s31
	s_nop 0
	global_load_lds_dwordx4 v[146:147], off
	v_lshl_add_u64 v[146:147], v[172:173], 0, s[24:25]
	s_mov_b32 m0, s33
	s_nop 0
	global_load_lds_dwordx4 v[146:147], off
	s_waitcnt vmcnt(8)
	s_waitcnt lgkmcnt(0)
	s_setprio 1
	s_barrier
	v_mfma_f32_16x16x32_bf16 v[62:65], v[130:133], v[204:207], v[62:65]
	v_mfma_f32_16x16x32_bf16 v[58:61], v[174:177], v[204:207], v[58:61]
	v_mfma_f32_16x16x32_bf16 v[46:49], v[130:133], v[212:215], v[46:49]
	v_mfma_f32_16x16x32_bf16 v[42:45], v[174:177], v[212:215], v[42:45]
	v_mfma_f32_16x16x32_bf16 v[30:33], v[130:133], v[220:223], v[30:33]
	v_mfma_f32_16x16x32_bf16 v[26:29], v[174:177], v[220:223], v[26:29]
	v_mfma_f32_16x16x32_bf16 v[14:17], v[130:133], v[228:231], v[14:17]
	v_mfma_f32_16x16x32_bf16 v[10:13], v[174:177], v[228:231], v[10:13]
	v_mfma_f32_16x16x32_bf16 v[62:65], v[156:159], v[208:211], v[62:65]
	v_mfma_f32_16x16x32_bf16 v[58:61], v[178:181], v[208:211], v[58:61]
	v_mfma_f32_16x16x32_bf16 v[46:49], v[156:159], v[216:219], v[46:49]
	v_mfma_f32_16x16x32_bf16 v[42:45], v[178:181], v[216:219], v[42:45]
	v_mfma_f32_16x16x32_bf16 v[30:33], v[156:159], v[224:227], v[30:33]
	v_mfma_f32_16x16x32_bf16 v[26:29], v[178:181], v[224:227], v[26:29]
	v_mfma_f32_16x16x32_bf16 v[14:17], v[156:159], v[232:235], v[14:17]
	v_mfma_f32_16x16x32_bf16 v[10:13], v[178:181], v[232:235], v[10:13]
	v_mfma_f32_16x16x32_bf16 v[54:57], v[182:185], v[204:207], v[54:57]
	v_mfma_f32_16x16x32_bf16 v[50:53], v[190:193], v[204:207], v[50:53]
	v_mfma_f32_16x16x32_bf16 v[38:41], v[182:185], v[212:215], v[38:41]
	v_mfma_f32_16x16x32_bf16 v[34:37], v[190:193], v[212:215], v[34:37]
	v_mfma_f32_16x16x32_bf16 v[22:25], v[182:185], v[220:223], v[22:25]
	v_mfma_f32_16x16x32_bf16 v[18:21], v[190:193], v[220:223], v[18:21]
	v_mfma_f32_16x16x32_bf16 v[6:9], v[182:185], v[228:231], v[6:9]
	v_mfma_f32_16x16x32_bf16 v[2:5], v[190:193], v[228:231], v[2:5]
	v_mfma_f32_16x16x32_bf16 v[54:57], v[186:189], v[208:211], v[54:57]
	v_mfma_f32_16x16x32_bf16 v[50:53], v[194:197], v[208:211], v[50:53]
	v_mfma_f32_16x16x32_bf16 v[38:41], v[186:189], v[216:219], v[38:41]
	v_mfma_f32_16x16x32_bf16 v[34:37], v[194:197], v[216:219], v[34:37]
	v_mfma_f32_16x16x32_bf16 v[22:25], v[186:189], v[224:227], v[22:25]
	v_mfma_f32_16x16x32_bf16 v[18:21], v[194:197], v[224:227], v[18:21]
	v_mfma_f32_16x16x32_bf16 v[6:9], v[186:189], v[232:235], v[6:9]
	v_mfma_f32_16x16x32_bf16 v[2:5], v[194:197], v[232:235], v[2:5]
	s_barrier
	s_setprio 0
	s_add_u32 s16, s16, 0x100
	s_addc_u32 s17, s17, 0
	s_add_u32 s56, s56, 0x100
	s_addc_u32 s57, s57, 0
	s_cmp_ge_i32 s72, s3
	s_mov_b32 s42, s72
	s_cbranch_scc0 .LBB7_1196
	s_branch .Lpeelx_1196

.LBB7_1199:
	v_and_b32_e32 v190, 0x30, v163
	v_lshl_add_u32 v190, v149, 6, v190
	v_add_u32_e32 v190, 0x20000, v190
	ds_read_b128 v[204:207], v190
	ds_read_b128 v[208:211], v190 offset:1024
	ds_read_b128 v[212:215], v190 offset:2048
	ds_read_b128 v[216:219], v190 offset:3072
	ds_read_b128 v[220:223], v190 offset:8192
	ds_read_b128 v[224:227], v190 offset:9216
	ds_read_b128 v[228:231], v190 offset:10240
	ds_read_b128 v[232:235], v190 offset:11264
	v_and_b32_e32 v131, 64, v163
	v_xor_b32_e32 v130, 16, v163
	v_add_u32_e32 v131, 64, v131
	v_cmp_lt_i32_e32 vcc, v130, v131
	v_lshl_add_u32 v146, s10, 8, v149
	v_ashrrev_i32_e32 v147, 31, v146
	v_cndmask_b32_e32 v130, v163, v130, vcc
	v_lshlrev_b32_e32 v183, 2, v130
	v_xor_b32_e32 v130, 32, v163
	v_cmp_lt_i32_e32 vcc, v130, v131
	s_mov_b32 s10, 0x358637bd
	v_mov_b64_e32 v[178:179], s[10:11]
	v_cndmask_b32_e32 v130, v163, v130, vcc
	v_lshlrev_b32_e32 v175, 2, v130
	v_lshlrev_b64 v[130:131], 6, v[146:147]
	v_lshl_add_u64 v[130:131], v[140:141], 0, v[130:131]
	v_add_u32_e32 v180, 0x80, v146
	v_ashrrev_i32_e32 v181, 31, v180
	v_add_u32_e32 v176, 0x90, v146
	v_ashrrev_i32_e32 v177, 31, v176
	v_add_u32_e32 v186, 0xa0, v146
	v_ashrrev_i32_e32 v187, 31, v186
	v_add_u32_e32 v184, 0xb0, v146
	v_ashrrev_i32_e32 v185, 31, v184
	s_mov_b64 s[16:17], -1
	s_waitcnt lgkmcnt(0)
	v_mov_b64_e32 v[130:131], v[204:205]
	v_mov_b64_e32 v[132:133], v[206:207]
	v_mov_b32_e32 v150, v131
	v_mov_b32_e32 v151, v132
	v_mov_b32_e32 v131, v133
	v_pk_add_f32 v[156:157], v[150:151], v[130:131]
	v_or_b32_e32 v150, 16, v146
	v_ashrrev_i32_e32 v151, 31, v150
	v_lshlrev_b64 v[130:131], 6, v[150:151]
	v_lshl_add_u64 v[130:131], v[140:141], 0, v[130:131]
	v_mov_b64_e32 v[130:131], v[208:209]
	v_mov_b64_e32 v[132:133], v[210:211]
	v_mov_b32_e32 v158, v131
	v_mov_b32_e32 v159, v132
	v_mov_b32_e32 v131, v133
	v_pk_add_f32 v[130:131], v[158:159], v[130:131]
	v_mov_b32_e32 v133, v156
	v_mov_b32_e32 v132, v130
	v_mov_b32_e32 v156, v131
	v_pk_add_f32 v[130:131], v[132:133], v[156:157]
	v_mov_b32_e32 v133, v131
	s_nop 1
	v_permlane16_swap_b32_e32 v131, v133
	v_mov_b32_e32 v132, v130
	s_nop 1
	v_permlane16_swap_b32_e32 v130, v132
	v_or_b32_e32 v158, 32, v146
	v_ashrrev_i32_e32 v159, 31, v158
	s_waitcnt lgkmcnt(0)
	v_pk_add_f32 v[130:131], v[130:131], v[132:133]
	v_mov_b32_e32 v133, v131
	s_nop 1
	v_permlane32_swap_b32_e32 v131, v133
	v_mov_b32_e32 v132, v130
	s_nop 1
	v_permlane32_swap_b32_e32 v130, v132
	s_waitcnt lgkmcnt(0)
	v_pk_add_f32 v[130:131], v[130:131], v[132:133]
	s_nop 0
	v_pk_fma_f32 v[130:131], v[130:131], s[26:27], v[178:179] op_sel_hi:[1,0,0]
	s_nop 0
	v_mul_f32_e32 v132, 0x4b800000, v131
	v_cmp_gt_f32_e64 s[42:43], s11, v131
	v_cmp_gt_f32_e32 vcc, s11, v130
	s_nop 0
	v_cndmask_b32_e64 v131, v131, v132, s[42:43]
	v_rsq_f32_e32 v131, v131
	s_nop 0
	v_mul_f32_e32 v132, 0x45800000, v131
	v_cndmask_b32_e64 v152, v131, v132, s[42:43]
	v_mul_f32_e32 v131, 0x4b800000, v130
	v_cndmask_b32_e32 v130, v130, v131, vcc
	v_rsq_f32_e32 v130, v130
	v_pk_mul_f32 v[128:129], v[128:129], v[152:153] op_sel_hi:[1,0]
	v_pk_mul_f32 v[126:127], v[126:127], v[152:153] op_sel_hi:[1,0]
	v_pk_mul_f32 v[120:121], v[120:121], v[152:153] op_sel_hi:[1,0]
	v_mul_f32_e32 v131, 0x45800000, v130
	v_cndmask_b32_e32 v148, v130, v131, vcc
	v_lshlrev_b64 v[130:131], 6, v[158:159]
	v_lshl_add_u64 v[130:131], v[140:141], 0, v[130:131]
	v_pk_mul_f32 v[118:119], v[118:119], v[152:153] op_sel_hi:[1,0]
	v_pk_mul_f32 v[112:113], v[112:113], v[148:149] op_sel_hi:[1,0]
	v_pk_mul_f32 v[110:111], v[110:111], v[148:149] op_sel_hi:[1,0]
	v_pk_mul_f32 v[104:105], v[104:105], v[148:149] op_sel_hi:[1,0]
	v_pk_mul_f32 v[102:103], v[102:103], v[148:149] op_sel_hi:[1,0]
	v_mov_b64_e32 v[130:131], v[212:213]
	v_mov_b64_e32 v[132:133], v[214:215]
	v_mov_b32_e32 v156, v131
	v_mov_b32_e32 v157, v132
	v_mov_b32_e32 v131, v133
	v_pk_add_f32 v[170:171], v[156:157], v[130:131]
	v_or_b32_e32 v156, 48, v146
	v_ashrrev_i32_e32 v157, 31, v156
	v_lshlrev_b64 v[130:131], 6, v[156:157]
	v_lshl_add_u64 v[130:131], v[140:141], 0, v[130:131]
	v_lshlrev_b64 v[146:147], 11, v[146:147]
	v_mov_b64_e32 v[130:131], v[216:217]
	v_mov_b64_e32 v[132:133], v[218:219]
	v_mov_b32_e32 v172, v131
	v_mov_b32_e32 v173, v132
	v_mov_b32_e32 v131, v133
	v_pk_add_f32 v[130:131], v[172:173], v[130:131]
	v_mov_b32_e32 v133, v170
	v_mov_b32_e32 v132, v130
	v_mov_b32_e32 v170, v131
	v_pk_add_f32 v[130:131], v[132:133], v[170:171]
	v_mov_b32_e32 v133, v131
	s_nop 1
	v_permlane16_swap_b32_e32 v131, v133
	v_mov_b32_e32 v132, v130
	s_nop 1
	v_permlane16_swap_b32_e32 v130, v132
	s_waitcnt lgkmcnt(0)
	v_pk_add_f32 v[130:131], v[130:131], v[132:133]
	v_mov_b32_e32 v133, v131
	s_nop 1
	v_permlane32_swap_b32_e32 v131, v133
	v_mov_b32_e32 v132, v130
	s_nop 1
	v_permlane32_swap_b32_e32 v130, v132
	s_waitcnt lgkmcnt(0)
	v_pk_add_f32 v[130:131], v[130:131], v[132:133]
	s_nop 0
	v_pk_fma_f32 v[130:131], v[130:131], s[26:27], v[178:179] op_sel_hi:[1,0,0]
	s_nop 0
	v_mul_f32_e32 v132, 0x4b800000, v131
	v_cmp_gt_f32_e64 s[42:43], s11, v131
	v_cmp_gt_f32_e32 vcc, s11, v130
	s_nop 0
	v_cndmask_b32_e64 v131, v131, v132, s[42:43]
	v_rsq_f32_e32 v131, v131
	s_nop 0
	v_mul_f32_e32 v132, 0x45800000, v131
	v_cndmask_b32_e64 v174, v131, v132, s[42:43]
	v_mul_f32_e32 v131, 0x4b800000, v130
	v_cndmask_b32_e32 v130, v130, v131, vcc
	v_rsq_f32_e32 v130, v130
	v_pk_mul_f32 v[96:97], v[96:97], v[174:175] op_sel_hi:[1,0]
	v_pk_mul_f32 v[94:95], v[94:95], v[174:175] op_sel_hi:[1,0]
	v_pk_mul_f32 v[88:89], v[88:89], v[174:175] op_sel_hi:[1,0]
	v_mul_f32_e32 v131, 0x45800000, v130
	v_cndmask_b32_e32 v154, v130, v131, vcc
	v_lshlrev_b64 v[130:131], 6, v[180:181]
	v_lshl_add_u64 v[130:131], v[140:141], 0, v[130:131]
	v_pk_mul_f32 v[86:87], v[86:87], v[174:175] op_sel_hi:[1,0]
	v_pk_mul_f32 v[80:81], v[80:81], v[154:155] op_sel_hi:[1,0]
	v_pk_mul_f32 v[78:79], v[78:79], v[154:155] op_sel_hi:[1,0]
	v_pk_mul_f32 v[72:73], v[72:73], v[154:155] op_sel_hi:[1,0]
	v_pk_mul_f32 v[70:71], v[70:71], v[154:155] op_sel_hi:[1,0]
	v_mov_b64_e32 v[130:131], v[220:221]
	v_mov_b64_e32 v[132:133], v[222:223]
	v_mov_b32_e32 v170, v131
	v_mov_b32_e32 v171, v132
	v_mov_b32_e32 v131, v133
	v_pk_add_f32 v[170:171], v[170:171], v[130:131]
	v_lshlrev_b64 v[130:131], 6, v[176:177]
	v_lshl_add_u64 v[130:131], v[140:141], 0, v[130:131]
	v_mov_b64_e32 v[130:131], v[224:225]
	v_mov_b64_e32 v[132:133], v[226:227]
	v_mov_b32_e32 v172, v131
	v_mov_b32_e32 v173, v132
	v_mov_b32_e32 v131, v133
	v_pk_add_f32 v[130:131], v[172:173], v[130:131]
	v_mov_b32_e32 v133, v170
	v_mov_b32_e32 v132, v130
	v_mov_b32_e32 v170, v131
	v_pk_add_f32 v[130:131], v[132:133], v[170:171]
	v_mov_b32_e32 v133, v131
	s_nop 1
	v_permlane16_swap_b32_e32 v131, v133
	v_mov_b32_e32 v132, v130
	s_nop 1
	v_permlane16_swap_b32_e32 v130, v132
	v_lshl_add_u64 v[172:173], s[94:95], 0, v[146:147]
	s_waitcnt lgkmcnt(0)
	v_pk_add_f32 v[130:131], v[130:131], v[132:133]
	v_mov_b32_e32 v133, v131
	s_nop 1
	v_permlane32_swap_b32_e32 v131, v133
	v_mov_b32_e32 v132, v130
	s_nop 1
	v_permlane32_swap_b32_e32 v130, v132
	s_waitcnt lgkmcnt(0)
	v_pk_add_f32 v[130:131], v[130:131], v[132:133]
	s_nop 0
	v_pk_fma_f32 v[130:131], v[130:131], s[26:27], v[178:179] op_sel_hi:[1,0,0]
	s_nop 0
	v_mul_f32_e32 v132, 0x4b800000, v131
	v_cmp_gt_f32_e64 s[42:43], s11, v131
	v_cmp_gt_f32_e32 vcc, s11, v130
	s_nop 0
	v_cndmask_b32_e64 v131, v131, v132, s[42:43]
	v_rsq_f32_e32 v131, v131
	s_nop 0
	v_mul_f32_e32 v132, 0x45800000, v131
	v_cndmask_b32_e64 v182, v131, v132, s[42:43]
	v_mul_f32_e32 v131, 0x4b800000, v130
	v_cndmask_b32_e32 v130, v130, v131, vcc
	v_rsq_f32_e32 v130, v130
	v_pk_mul_f32 v[64:65], v[64:65], v[182:183] op_sel_hi:[1,0]
	v_pk_mul_f32 v[62:63], v[62:63], v[182:183] op_sel_hi:[1,0]
	v_pk_mul_f32 v[56:57], v[56:57], v[182:183] op_sel_hi:[1,0]
	v_mul_f32_e32 v131, 0x45800000, v130
	v_cndmask_b32_e32 v160, v130, v131, vcc
	v_lshlrev_b64 v[130:131], 6, v[186:187]
	v_lshl_add_u64 v[130:131], v[140:141], 0, v[130:131]
	v_pk_mul_f32 v[54:55], v[54:55], v[182:183] op_sel_hi:[1,0]
	v_pk_mul_f32 v[48:49], v[48:49], v[160:161] op_sel_hi:[1,0]
	v_pk_mul_f32 v[46:47], v[46:47], v[160:161] op_sel_hi:[1,0]
	v_pk_mul_f32 v[40:41], v[40:41], v[160:161] op_sel_hi:[1,0]
	v_pk_mul_f32 v[38:39], v[38:39], v[160:161] op_sel_hi:[1,0]
	v_mov_b64_e32 v[130:131], v[228:229]
	v_mov_b64_e32 v[132:133], v[230:231]
	v_mov_b32_e32 v170, v131
	v_mov_b32_e32 v171, v132
	v_mov_b32_e32 v131, v133
	v_pk_add_f32 v[188:189], v[170:171], v[130:131]
	v_lshlrev_b64 v[130:131], 6, v[184:185]
	v_lshl_add_u64 v[130:131], v[140:141], 0, v[130:131]
	v_mov_b64_e32 v[130:131], v[232:233]
	v_mov_b64_e32 v[132:133], v[234:235]
	v_mov_b32_e32 v170, v131
	v_mov_b32_e32 v171, v132
	v_mov_b32_e32 v131, v133
	v_pk_add_f32 v[130:131], v[170:171], v[130:131]
	v_lshl_or_b32 v170, s38, 8, v155
	v_mov_b32_e32 v132, v130
	v_mov_b32_e32 v133, v188
	v_mov_b32_e32 v188, v131
	v_ashrrev_i32_e32 v171, 31, v170
	v_pk_add_f32 v[130:131], v[132:133], v[188:189]
	v_lshlrev_b64 v[146:147], 1, v[170:171]
	v_mov_b32_e32 v133, v131
	s_nop 1
	v_permlane16_swap_b32_e32 v131, v133
	v_mov_b32_e32 v132, v130
	s_nop 1
	v_permlane16_swap_b32_e32 v130, v132
	v_lshl_add_u64 v[170:171], v[172:173], 0, v[146:147]
	v_pk_mul_f32 v[172:173], v[124:125], v[152:153] op_sel_hi:[1,0]
	v_pk_mul_f32 v[124:125], v[122:123], v[152:153] op_sel_hi:[1,0]
	v_cvt_pk_bf16_f32 v122, v126, v127
	v_cvt_pk_bf16_f32 v123, v128, v129
	s_waitcnt lgkmcnt(0)
	v_pk_add_f32 v[130:131], v[130:131], v[132:133]
	v_cvt_pk_bf16_f32 v124, v124, v125
	v_cvt_pk_bf16_f32 v125, v172, v173
	global_store_dwordx4 v[170:171], v[122:125], off
	v_mov_b32_e32 v133, v131
	s_nop 1
	v_permlane32_swap_b32_e32 v131, v133
	v_mov_b32_e32 v132, v130
	s_nop 1
	v_permlane32_swap_b32_e32 v130, v132
	v_pk_mul_f32 v[122:123], v[116:117], v[152:153] op_sel_hi:[1,0]
	v_pk_mul_f32 v[116:117], v[114:115], v[152:153] op_sel_hi:[1,0]
	v_cvt_pk_bf16_f32 v114, v118, v119
	v_cvt_pk_bf16_f32 v115, v120, v121
	s_waitcnt lgkmcnt(0)
	v_pk_add_f32 v[130:131], v[130:131], v[132:133]
	v_cvt_pk_bf16_f32 v116, v116, v117
	v_cvt_pk_bf16_f32 v117, v122, v123
	global_store_dwordx4 v[170:171], v[114:117], off offset:256
	v_pk_fma_f32 v[130:131], v[130:131], s[26:27], v[178:179] op_sel_hi:[1,0,0]
	s_nop 0
	v_lshlrev_b64 v[114:115], 11, v[150:151]
	v_lshl_add_u64 v[114:115], s[94:95], 0, v[114:115]
	v_lshl_add_u64 v[114:115], v[114:115], 0, v[146:147]
	v_pk_mul_f32 v[116:117], v[108:109], v[148:149] op_sel_hi:[1,0]
	v_pk_mul_f32 v[108:109], v[106:107], v[148:149] op_sel_hi:[1,0]
	v_cvt_pk_bf16_f32 v106, v110, v111
	v_cvt_pk_bf16_f32 v107, v112, v113
	v_mul_f32_e32 v132, 0x4b800000, v131
	v_cvt_pk_bf16_f32 v108, v108, v109
	v_cvt_pk_bf16_f32 v109, v116, v117
	global_store_dwordx4 v[114:115], v[106:109], off
	v_cmp_gt_f32_e64 s[42:43], s11, v131
	v_cmp_gt_f32_e32 vcc, s11, v130
	v_pk_mul_f32 v[106:107], v[100:101], v[148:149] op_sel_hi:[1,0]
	v_pk_mul_f32 v[100:101], v[98:99], v[148:149] op_sel_hi:[1,0]
	v_cvt_pk_bf16_f32 v98, v102, v103
	v_cvt_pk_bf16_f32 v99, v104, v105
	v_cndmask_b32_e64 v131, v131, v132, s[42:43]
	v_cvt_pk_bf16_f32 v100, v100, v101
	v_cvt_pk_bf16_f32 v101, v106, v107
	global_store_dwordx4 v[114:115], v[98:101], off offset:256
	v_rsq_f32_e32 v131, v131
	s_nop 0
	v_lshlrev_b64 v[98:99], 11, v[158:159]
	v_lshl_add_u64 v[98:99], s[94:95], 0, v[98:99]
	v_lshl_add_u64 v[98:99], v[98:99], 0, v[146:147]
	v_pk_mul_f32 v[100:101], v[92:93], v[174:175] op_sel_hi:[1,0]
	v_pk_mul_f32 v[92:93], v[90:91], v[174:175] op_sel_hi:[1,0]
	v_cvt_pk_bf16_f32 v90, v94, v95
	v_cvt_pk_bf16_f32 v91, v96, v97
	v_mul_f32_e32 v132, 0x45800000, v131
	v_cvt_pk_bf16_f32 v92, v92, v93
	v_cvt_pk_bf16_f32 v93, v100, v101
	global_store_dwordx4 v[98:99], v[90:93], off
	v_cndmask_b32_e64 v132, v131, v132, s[42:43]
	v_mul_f32_e32 v131, 0x4b800000, v130
	v_pk_mul_f32 v[90:91], v[84:85], v[174:175] op_sel_hi:[1,0]
	v_pk_mul_f32 v[84:85], v[82:83], v[174:175] op_sel_hi:[1,0]
	v_cvt_pk_bf16_f32 v82, v86, v87
	v_cvt_pk_bf16_f32 v83, v88, v89
	v_cndmask_b32_e32 v130, v130, v131, vcc
	v_cvt_pk_bf16_f32 v84, v84, v85
	v_cvt_pk_bf16_f32 v85, v90, v91
	global_store_dwordx4 v[98:99], v[82:85], off offset:256
	v_rsq_f32_e32 v130, v130
	v_pk_mul_f32 v[32:33], v[32:33], v[132:133] op_sel_hi:[1,0]
	v_lshlrev_b64 v[82:83], 11, v[156:157]
	v_lshl_add_u64 v[82:83], s[94:95], 0, v[82:83]
	v_lshl_add_u64 v[82:83], v[82:83], 0, v[146:147]
	v_pk_mul_f32 v[84:85], v[76:77], v[154:155] op_sel_hi:[1,0]
	v_pk_mul_f32 v[76:77], v[74:75], v[154:155] op_sel_hi:[1,0]
	v_cvt_pk_bf16_f32 v74, v78, v79
	v_cvt_pk_bf16_f32 v75, v80, v81
	v_pk_mul_f32 v[30:31], v[30:31], v[132:133] op_sel_hi:[1,0]
	v_cvt_pk_bf16_f32 v76, v76, v77
	v_cvt_pk_bf16_f32 v77, v84, v85
	global_store_dwordx4 v[82:83], v[74:77], off
	v_pk_mul_f32 v[24:25], v[24:25], v[132:133] op_sel_hi:[1,0]
	v_pk_mul_f32 v[22:23], v[22:23], v[132:133] op_sel_hi:[1,0]
	v_pk_mul_f32 v[74:75], v[68:69], v[154:155] op_sel_hi:[1,0]
	v_pk_mul_f32 v[68:69], v[66:67], v[154:155] op_sel_hi:[1,0]
	v_cvt_pk_bf16_f32 v66, v70, v71
	v_cvt_pk_bf16_f32 v67, v72, v73
	v_mul_f32_e32 v131, 0x45800000, v130
	v_cvt_pk_bf16_f32 v68, v68, v69
	v_cvt_pk_bf16_f32 v69, v74, v75
	global_store_dwordx4 v[82:83], v[66:69], off offset:256
	v_cndmask_b32_e32 v130, v130, v131, vcc
	v_pk_mul_f32 v[16:17], v[16:17], v[130:131] op_sel_hi:[1,0]
	v_lshlrev_b64 v[66:67], 11, v[180:181]
	v_lshl_add_u64 v[66:67], s[94:95], 0, v[66:67]
	v_lshl_add_u64 v[66:67], v[66:67], 0, v[146:147]
	v_pk_mul_f32 v[68:69], v[60:61], v[182:183] op_sel_hi:[1,0]
	v_pk_mul_f32 v[60:61], v[58:59], v[182:183] op_sel_hi:[1,0]
	v_cvt_pk_bf16_f32 v58, v62, v63
	v_cvt_pk_bf16_f32 v59, v64, v65
	v_pk_mul_f32 v[14:15], v[14:15], v[130:131] op_sel_hi:[1,0]
	v_cvt_pk_bf16_f32 v60, v60, v61
	v_cvt_pk_bf16_f32 v61, v68, v69
	global_store_dwordx4 v[66:67], v[58:61], off
	v_pk_mul_f32 v[8:9], v[8:9], v[130:131] op_sel_hi:[1,0]
	v_pk_mul_f32 v[6:7], v[6:7], v[130:131] op_sel_hi:[1,0]
	v_pk_mul_f32 v[58:59], v[52:53], v[182:183] op_sel_hi:[1,0]
	v_pk_mul_f32 v[52:53], v[50:51], v[182:183] op_sel_hi:[1,0]
	v_cvt_pk_bf16_f32 v50, v54, v55
	v_cvt_pk_bf16_f32 v51, v56, v57
	s_andn2_b64 vcc, exec, s[40:41]
	v_cvt_pk_bf16_f32 v52, v52, v53
	v_cvt_pk_bf16_f32 v53, v58, v59
	global_store_dwordx4 v[66:67], v[50:53], off offset:256
	s_nop 1
	v_lshlrev_b64 v[50:51], 11, v[176:177]
	v_lshl_add_u64 v[50:51], s[94:95], 0, v[50:51]
	v_lshl_add_u64 v[50:51], v[50:51], 0, v[146:147]
	v_pk_mul_f32 v[52:53], v[44:45], v[160:161] op_sel_hi:[1,0]
	v_pk_mul_f32 v[44:45], v[42:43], v[160:161] op_sel_hi:[1,0]
	v_cvt_pk_bf16_f32 v42, v46, v47
	v_cvt_pk_bf16_f32 v43, v48, v49
	s_nop 0
	v_cvt_pk_bf16_f32 v44, v44, v45
	v_cvt_pk_bf16_f32 v45, v52, v53
	global_store_dwordx4 v[50:51], v[42:45], off
	s_nop 1
	v_pk_mul_f32 v[42:43], v[36:37], v[160:161] op_sel_hi:[1,0]
	v_pk_mul_f32 v[36:37], v[34:35], v[160:161] op_sel_hi:[1,0]
	v_cvt_pk_bf16_f32 v34, v38, v39
	v_cvt_pk_bf16_f32 v35, v40, v41
	s_nop 0
	v_cvt_pk_bf16_f32 v36, v36, v37
	v_cvt_pk_bf16_f32 v37, v42, v43
	global_store_dwordx4 v[50:51], v[34:37], off offset:256
	s_nop 1
	v_lshlrev_b64 v[34:35], 11, v[186:187]
	v_lshl_add_u64 v[34:35], s[94:95], 0, v[34:35]
	v_lshl_add_u64 v[34:35], v[34:35], 0, v[146:147]
	v_pk_mul_f32 v[36:37], v[28:29], v[132:133] op_sel_hi:[1,0]
	v_pk_mul_f32 v[28:29], v[26:27], v[132:133] op_sel_hi:[1,0]
	v_cvt_pk_bf16_f32 v26, v30, v31
	v_cvt_pk_bf16_f32 v27, v32, v33
	s_nop 0
	v_cvt_pk_bf16_f32 v28, v28, v29
	v_cvt_pk_bf16_f32 v29, v36, v37
	global_store_dwordx4 v[34:35], v[26:29], off
	s_nop 1
	v_pk_mul_f32 v[26:27], v[20:21], v[132:133] op_sel_hi:[1,0]
	v_pk_mul_f32 v[20:21], v[18:19], v[132:133] op_sel_hi:[1,0]
	v_cvt_pk_bf16_f32 v18, v22, v23
	v_cvt_pk_bf16_f32 v19, v24, v25
	s_nop 0
	v_cvt_pk_bf16_f32 v20, v20, v21
	v_cvt_pk_bf16_f32 v21, v26, v27
	global_store_dwordx4 v[34:35], v[18:21], off offset:256
	s_nop 1
	v_lshlrev_b64 v[18:19], 11, v[184:185]
	v_lshl_add_u64 v[18:19], s[94:95], 0, v[18:19]
	v_lshl_add_u64 v[18:19], v[18:19], 0, v[146:147]
	v_pk_mul_f32 v[20:21], v[12:13], v[130:131] op_sel_hi:[1,0]
	v_pk_mul_f32 v[12:13], v[10:11], v[130:131] op_sel_hi:[1,0]
	v_cvt_pk_bf16_f32 v10, v14, v15
	v_cvt_pk_bf16_f32 v11, v16, v17
	s_nop 0
	v_cvt_pk_bf16_f32 v12, v12, v13
	v_cvt_pk_bf16_f32 v13, v20, v21
	global_store_dwordx4 v[18:19], v[10:13], off
	s_nop 1
	v_pk_mul_f32 v[10:11], v[4:5], v[130:131] op_sel_hi:[1,0]
	v_pk_mul_f32 v[4:5], v[2:3], v[130:131] op_sel_hi:[1,0]
	v_cvt_pk_bf16_f32 v2, v6, v7
	v_cvt_pk_bf16_f32 v3, v8, v9
	s_nop 0
	v_cvt_pk_bf16_f32 v4, v4, v5
	v_cvt_pk_bf16_f32 v5, v10, v11
	global_store_dwordx4 v[18:19], v[2:5], off offset:256
	s_cbranch_vccnz .LBB7_1187
	s_andn2_b64 vcc, exec, s[0:1]
	s_cbranch_vccnz .LBB7_1186
	s_barrier
	s_branch .LBB7_1186
